# hand-written SwiGLU epilogue for both gate/up GEMMs: packed f32 mul/add, batched exp/rcp, no hazard nops (530 -> 340 instructions per tile)
# speedup vs baseline: 1.0082x; 1.0011x over previous
.LBB0_1175:
	v_readlane_b32 s0, v249, 6
	v_lshl_or_b32 v144, s52, 7, v147
	v_readlane_b32 s1, v249, 7
	v_lshl_add_u32 v153, s53, 8, v146
	v_ashrrev_i32_e32 v145, 31, v144
	v_mov_b64_e32 v[142:143], s[0:1]
	v_mad_u64_u32 v[154:155], s[20:21], v153, s41, v[142:143]
	v_lshlrev_b64 v[144:145], 1, v[144:145]
	v_lshl_add_u64 v[154:155], v[154:155], 0, v[144:145]
	v_mov_b32_e32 v192, 0xbfb8aa3b
	v_mov_b32_e32 v193, 0xbfb8aa3b
	v_mov_b32_e32 v194, 1.0
	v_mov_b32_e32 v195, 1.0
	s_mov_b64 s[22:23], 0x56000
	s_mov_b64 s[24:25], 0x1ae000
	v_pk_mul_f32 v[176:177], v[126:127], v[192:193]
	v_pk_mul_f32 v[178:179], v[128:129], v[192:193]
	v_pk_mul_f32 v[180:181], v[118:119], v[192:193]
	v_pk_mul_f32 v[182:183], v[120:121], v[192:193]
	v_exp_f32_e32 v176, v176
	v_exp_f32_e32 v177, v177
	v_exp_f32_e32 v178, v178
	v_exp_f32_e32 v179, v179
	v_exp_f32_e32 v180, v180
	v_exp_f32_e32 v181, v181
	v_exp_f32_e32 v182, v182
	v_exp_f32_e32 v183, v183
	v_pk_add_f32 v[176:177], v[176:177], v[194:195]
	v_pk_add_f32 v[178:179], v[178:179], v[194:195]
	v_pk_add_f32 v[180:181], v[180:181], v[194:195]
	v_pk_add_f32 v[182:183], v[182:183], v[194:195]
	v_rcp_f32_e32 v176, v176
	v_rcp_f32_e32 v177, v177
	v_rcp_f32_e32 v178, v178
	v_rcp_f32_e32 v179, v179
	v_rcp_f32_e32 v180, v180
	v_rcp_f32_e32 v181, v181
	v_rcp_f32_e32 v182, v182
	v_rcp_f32_e32 v183, v183
	v_lshl_add_u64 v[156:157], v[154:155], 0, s[22:23]
	v_pk_mul_f32 v[126:127], v[126:127], v[176:177]
	v_pk_mul_f32 v[128:129], v[128:129], v[178:179]
	v_pk_mul_f32 v[118:119], v[118:119], v[180:181]
	v_pk_mul_f32 v[120:121], v[120:121], v[182:183]
	v_pk_mul_f32 v[126:127], v[126:127], v[122:123]
	v_pk_mul_f32 v[128:129], v[128:129], v[124:125]
	v_pk_mul_f32 v[118:119], v[118:119], v[114:115]
	v_pk_mul_f32 v[120:121], v[120:121], v[116:117]
	v_cvt_pk_bf16_f32 v184, v126, v127
	v_cvt_pk_bf16_f32 v185, v128, v129
	v_cvt_pk_bf16_f32 v186, v118, v119
	v_cvt_pk_bf16_f32 v187, v120, v121
	global_store_dwordx4 v[154:155], v[184:187], off
	v_pk_mul_f32 v[176:177], v[110:111], v[192:193]
	v_pk_mul_f32 v[178:179], v[112:113], v[192:193]
	v_pk_mul_f32 v[180:181], v[102:103], v[192:193]
	v_pk_mul_f32 v[182:183], v[104:105], v[192:193]
	v_exp_f32_e32 v176, v176
	v_exp_f32_e32 v177, v177
	v_exp_f32_e32 v178, v178
	v_exp_f32_e32 v179, v179
	v_exp_f32_e32 v180, v180
	v_exp_f32_e32 v181, v181
	v_exp_f32_e32 v182, v182
	v_exp_f32_e32 v183, v183
	v_pk_add_f32 v[176:177], v[176:177], v[194:195]
	v_pk_add_f32 v[178:179], v[178:179], v[194:195]
	v_pk_add_f32 v[180:181], v[180:181], v[194:195]
	v_pk_add_f32 v[182:183], v[182:183], v[194:195]
	v_rcp_f32_e32 v176, v176
	v_rcp_f32_e32 v177, v177
	v_rcp_f32_e32 v178, v178
	v_rcp_f32_e32 v179, v179
	v_rcp_f32_e32 v180, v180
	v_rcp_f32_e32 v181, v181
	v_rcp_f32_e32 v182, v182
	v_rcp_f32_e32 v183, v183
	v_lshl_add_u64 v[154:155], v[156:157], 0, s[22:23]
	v_pk_mul_f32 v[110:111], v[110:111], v[176:177]
	v_pk_mul_f32 v[112:113], v[112:113], v[178:179]
	v_pk_mul_f32 v[102:103], v[102:103], v[180:181]
	v_pk_mul_f32 v[104:105], v[104:105], v[182:183]
	v_pk_mul_f32 v[110:111], v[110:111], v[106:107]
	v_pk_mul_f32 v[112:113], v[112:113], v[108:109]
	v_pk_mul_f32 v[102:103], v[102:103], v[98:99]
	v_pk_mul_f32 v[104:105], v[104:105], v[100:101]
	v_cvt_pk_bf16_f32 v188, v110, v111
	v_cvt_pk_bf16_f32 v189, v112, v113
	v_cvt_pk_bf16_f32 v190, v102, v103
	v_cvt_pk_bf16_f32 v191, v104, v105
	global_store_dwordx4 v[156:157], v[188:191], off
	v_pk_mul_f32 v[176:177], v[94:95], v[192:193]
	v_pk_mul_f32 v[178:179], v[96:97], v[192:193]
	v_pk_mul_f32 v[180:181], v[86:87], v[192:193]
	v_pk_mul_f32 v[182:183], v[88:89], v[192:193]
	v_exp_f32_e32 v176, v176
	v_exp_f32_e32 v177, v177
	v_exp_f32_e32 v178, v178
	v_exp_f32_e32 v179, v179
	v_exp_f32_e32 v180, v180
	v_exp_f32_e32 v181, v181
	v_exp_f32_e32 v182, v182
	v_exp_f32_e32 v183, v183
	v_pk_add_f32 v[176:177], v[176:177], v[194:195]
	v_pk_add_f32 v[178:179], v[178:179], v[194:195]
	v_pk_add_f32 v[180:181], v[180:181], v[194:195]
	v_pk_add_f32 v[182:183], v[182:183], v[194:195]
	v_rcp_f32_e32 v176, v176
	v_rcp_f32_e32 v177, v177
	v_rcp_f32_e32 v178, v178
	v_rcp_f32_e32 v179, v179
	v_rcp_f32_e32 v180, v180
	v_rcp_f32_e32 v181, v181
	v_rcp_f32_e32 v182, v182
	v_rcp_f32_e32 v183, v183
	v_lshl_add_u64 v[156:157], v[154:155], 0, s[22:23]
	v_pk_mul_f32 v[94:95], v[94:95], v[176:177]
	v_pk_mul_f32 v[96:97], v[96:97], v[178:179]
	v_pk_mul_f32 v[86:87], v[86:87], v[180:181]
	v_pk_mul_f32 v[88:89], v[88:89], v[182:183]
	v_pk_mul_f32 v[94:95], v[94:95], v[90:91]
	v_pk_mul_f32 v[96:97], v[96:97], v[92:93]
	v_pk_mul_f32 v[86:87], v[86:87], v[82:83]
	v_pk_mul_f32 v[88:89], v[88:89], v[84:85]
	v_cvt_pk_bf16_f32 v184, v94, v95
	v_cvt_pk_bf16_f32 v185, v96, v97
	v_cvt_pk_bf16_f32 v186, v86, v87
	v_cvt_pk_bf16_f32 v187, v88, v89
	global_store_dwordx4 v[154:155], v[184:187], off
	v_pk_mul_f32 v[176:177], v[78:79], v[192:193]
	v_pk_mul_f32 v[178:179], v[80:81], v[192:193]
	v_pk_mul_f32 v[180:181], v[70:71], v[192:193]
	v_pk_mul_f32 v[182:183], v[72:73], v[192:193]
	v_exp_f32_e32 v176, v176
	v_exp_f32_e32 v177, v177
	v_exp_f32_e32 v178, v178
	v_exp_f32_e32 v179, v179
	v_exp_f32_e32 v180, v180
	v_exp_f32_e32 v181, v181
	v_exp_f32_e32 v182, v182
	v_exp_f32_e32 v183, v183
	v_pk_add_f32 v[176:177], v[176:177], v[194:195]
	v_pk_add_f32 v[178:179], v[178:179], v[194:195]
	v_pk_add_f32 v[180:181], v[180:181], v[194:195]
	v_pk_add_f32 v[182:183], v[182:183], v[194:195]
	v_rcp_f32_e32 v176, v176
	v_rcp_f32_e32 v177, v177
	v_rcp_f32_e32 v178, v178
	v_rcp_f32_e32 v179, v179
	v_rcp_f32_e32 v180, v180
	v_rcp_f32_e32 v181, v181
	v_rcp_f32_e32 v182, v182
	v_rcp_f32_e32 v183, v183
	v_lshl_add_u64 v[154:155], v[156:157], 0, s[24:25]
	v_pk_mul_f32 v[78:79], v[78:79], v[176:177]
	v_pk_mul_f32 v[80:81], v[80:81], v[178:179]
	v_pk_mul_f32 v[70:71], v[70:71], v[180:181]
	v_pk_mul_f32 v[72:73], v[72:73], v[182:183]
	v_pk_mul_f32 v[78:79], v[78:79], v[74:75]
	v_pk_mul_f32 v[80:81], v[80:81], v[76:77]
	v_pk_mul_f32 v[70:71], v[70:71], v[66:67]
	v_pk_mul_f32 v[72:73], v[72:73], v[68:69]
	v_cvt_pk_bf16_f32 v188, v78, v79
	v_cvt_pk_bf16_f32 v189, v80, v81
	v_cvt_pk_bf16_f32 v190, v70, v71
	v_cvt_pk_bf16_f32 v191, v72, v73
	global_store_dwordx4 v[156:157], v[188:191], off
	v_pk_mul_f32 v[176:177], v[62:63], v[192:193]
	v_pk_mul_f32 v[178:179], v[64:65], v[192:193]
	v_pk_mul_f32 v[180:181], v[54:55], v[192:193]
	v_pk_mul_f32 v[182:183], v[56:57], v[192:193]
	v_exp_f32_e32 v176, v176
	v_exp_f32_e32 v177, v177
	v_exp_f32_e32 v178, v178
	v_exp_f32_e32 v179, v179
	v_exp_f32_e32 v180, v180
	v_exp_f32_e32 v181, v181
	v_exp_f32_e32 v182, v182
	v_exp_f32_e32 v183, v183
	v_pk_add_f32 v[176:177], v[176:177], v[194:195]
	v_pk_add_f32 v[178:179], v[178:179], v[194:195]
	v_pk_add_f32 v[180:181], v[180:181], v[194:195]
	v_pk_add_f32 v[182:183], v[182:183], v[194:195]
	v_rcp_f32_e32 v176, v176
	v_rcp_f32_e32 v177, v177
	v_rcp_f32_e32 v178, v178
	v_rcp_f32_e32 v179, v179
	v_rcp_f32_e32 v180, v180
	v_rcp_f32_e32 v181, v181
	v_rcp_f32_e32 v182, v182
	v_rcp_f32_e32 v183, v183
	v_lshl_add_u64 v[156:157], v[154:155], 0, s[22:23]
	v_pk_mul_f32 v[62:63], v[62:63], v[176:177]
	v_pk_mul_f32 v[64:65], v[64:65], v[178:179]
	v_pk_mul_f32 v[54:55], v[54:55], v[180:181]
	v_pk_mul_f32 v[56:57], v[56:57], v[182:183]
	v_pk_mul_f32 v[62:63], v[62:63], v[58:59]
	v_pk_mul_f32 v[64:65], v[64:65], v[60:61]
	v_pk_mul_f32 v[54:55], v[54:55], v[50:51]
	v_pk_mul_f32 v[56:57], v[56:57], v[52:53]
	v_cvt_pk_bf16_f32 v184, v62, v63
	v_cvt_pk_bf16_f32 v185, v64, v65
	v_cvt_pk_bf16_f32 v186, v54, v55
	v_cvt_pk_bf16_f32 v187, v56, v57
	global_store_dwordx4 v[154:155], v[184:187], off
	v_pk_mul_f32 v[176:177], v[46:47], v[192:193]
	v_pk_mul_f32 v[178:179], v[48:49], v[192:193]
	v_pk_mul_f32 v[180:181], v[38:39], v[192:193]
	v_pk_mul_f32 v[182:183], v[40:41], v[192:193]
	v_exp_f32_e32 v176, v176
	v_exp_f32_e32 v177, v177
	v_exp_f32_e32 v178, v178
	v_exp_f32_e32 v179, v179
	v_exp_f32_e32 v180, v180
	v_exp_f32_e32 v181, v181
	v_exp_f32_e32 v182, v182
	v_exp_f32_e32 v183, v183
	v_pk_add_f32 v[176:177], v[176:177], v[194:195]
	v_pk_add_f32 v[178:179], v[178:179], v[194:195]
	v_pk_add_f32 v[180:181], v[180:181], v[194:195]
	v_pk_add_f32 v[182:183], v[182:183], v[194:195]
	v_rcp_f32_e32 v176, v176
	v_rcp_f32_e32 v177, v177
	v_rcp_f32_e32 v178, v178
	v_rcp_f32_e32 v179, v179
	v_rcp_f32_e32 v180, v180
	v_rcp_f32_e32 v181, v181
	v_rcp_f32_e32 v182, v182
	v_rcp_f32_e32 v183, v183
	v_lshl_add_u64 v[154:155], v[156:157], 0, s[22:23]
	v_pk_mul_f32 v[46:47], v[46:47], v[176:177]
	v_pk_mul_f32 v[48:49], v[48:49], v[178:179]
	v_pk_mul_f32 v[38:39], v[38:39], v[180:181]
	v_pk_mul_f32 v[40:41], v[40:41], v[182:183]
	v_pk_mul_f32 v[46:47], v[46:47], v[42:43]
	v_pk_mul_f32 v[48:49], v[48:49], v[44:45]
	v_pk_mul_f32 v[38:39], v[38:39], v[34:35]
	v_pk_mul_f32 v[40:41], v[40:41], v[36:37]
	v_cvt_pk_bf16_f32 v188, v46, v47
	v_cvt_pk_bf16_f32 v189, v48, v49
	v_cvt_pk_bf16_f32 v190, v38, v39
	v_cvt_pk_bf16_f32 v191, v40, v41
	global_store_dwordx4 v[156:157], v[188:191], off
	v_pk_mul_f32 v[176:177], v[30:31], v[192:193]
	v_pk_mul_f32 v[178:179], v[32:33], v[192:193]
	v_pk_mul_f32 v[180:181], v[22:23], v[192:193]
	v_pk_mul_f32 v[182:183], v[24:25], v[192:193]
	v_exp_f32_e32 v176, v176
	v_exp_f32_e32 v177, v177
	v_exp_f32_e32 v178, v178
	v_exp_f32_e32 v179, v179
	v_exp_f32_e32 v180, v180
	v_exp_f32_e32 v181, v181
	v_exp_f32_e32 v182, v182
	v_exp_f32_e32 v183, v183
	v_pk_add_f32 v[176:177], v[176:177], v[194:195]
	v_pk_add_f32 v[178:179], v[178:179], v[194:195]
	v_pk_add_f32 v[180:181], v[180:181], v[194:195]
	v_pk_add_f32 v[182:183], v[182:183], v[194:195]
	v_rcp_f32_e32 v176, v176
	v_rcp_f32_e32 v177, v177
	v_rcp_f32_e32 v178, v178
	v_rcp_f32_e32 v179, v179
	v_rcp_f32_e32 v180, v180
	v_rcp_f32_e32 v181, v181
	v_rcp_f32_e32 v182, v182
	v_rcp_f32_e32 v183, v183
	v_lshl_add_u64 v[156:157], v[154:155], 0, s[22:23]
	v_pk_mul_f32 v[30:31], v[30:31], v[176:177]
	v_pk_mul_f32 v[32:33], v[32:33], v[178:179]
	v_pk_mul_f32 v[22:23], v[22:23], v[180:181]
	v_pk_mul_f32 v[24:25], v[24:25], v[182:183]
	v_pk_mul_f32 v[30:31], v[30:31], v[26:27]
	v_pk_mul_f32 v[32:33], v[32:33], v[28:29]
	v_pk_mul_f32 v[22:23], v[22:23], v[18:19]
	v_pk_mul_f32 v[24:25], v[24:25], v[20:21]
	v_cvt_pk_bf16_f32 v184, v30, v31
	v_cvt_pk_bf16_f32 v185, v32, v33
	v_cvt_pk_bf16_f32 v186, v22, v23
	v_cvt_pk_bf16_f32 v187, v24, v25
	global_store_dwordx4 v[154:155], v[184:187], off
	v_pk_mul_f32 v[176:177], v[14:15], v[192:193]
	v_pk_mul_f32 v[178:179], v[16:17], v[192:193]
	v_pk_mul_f32 v[180:181], v[6:7], v[192:193]
	v_pk_mul_f32 v[182:183], v[8:9], v[192:193]
	v_exp_f32_e32 v176, v176
	v_exp_f32_e32 v177, v177
	v_exp_f32_e32 v178, v178
	v_exp_f32_e32 v179, v179
	v_exp_f32_e32 v180, v180
	v_exp_f32_e32 v181, v181
	v_exp_f32_e32 v182, v182
	v_exp_f32_e32 v183, v183
	v_pk_add_f32 v[176:177], v[176:177], v[194:195]
	v_pk_add_f32 v[178:179], v[178:179], v[194:195]
	v_pk_add_f32 v[180:181], v[180:181], v[194:195]
	v_pk_add_f32 v[182:183], v[182:183], v[194:195]
	v_rcp_f32_e32 v176, v176
	v_rcp_f32_e32 v177, v177
	v_rcp_f32_e32 v178, v178
	v_rcp_f32_e32 v179, v179
	v_rcp_f32_e32 v180, v180
	v_rcp_f32_e32 v181, v181
	v_rcp_f32_e32 v182, v182
	v_rcp_f32_e32 v183, v183
	s_nop 0
	v_pk_mul_f32 v[14:15], v[14:15], v[176:177]
	v_pk_mul_f32 v[16:17], v[16:17], v[178:179]
	v_pk_mul_f32 v[6:7], v[6:7], v[180:181]
	v_pk_mul_f32 v[8:9], v[8:9], v[182:183]
	v_pk_mul_f32 v[14:15], v[14:15], v[10:11]
	v_pk_mul_f32 v[16:17], v[16:17], v[12:13]
	v_pk_mul_f32 v[6:7], v[6:7], v[2:3]
	v_pk_mul_f32 v[8:9], v[8:9], v[4:5]
	v_cvt_pk_bf16_f32 v188, v14, v15
	v_cvt_pk_bf16_f32 v189, v16, v17
	v_cvt_pk_bf16_f32 v190, v6, v7
	v_cvt_pk_bf16_f32 v191, v8, v9
	global_store_dwordx4 v[156:157], v[188:191], off
	v_readlane_b32 s60, v250, 50
	v_readlane_b32 s72, v250, 62
	v_readlane_b32 s73, v250, 63
	v_readlane_b32 s74, v249, 0
	v_readlane_b32 s75, v249, 1
	v_readlane_b32 s61, v250, 51
	v_readlane_b32 s62, v250, 52
	v_readlane_b32 s63, v250, 53
	v_readlane_b32 s64, v250, 54
	v_readlane_b32 s65, v250, 55
	v_readlane_b32 s66, v250, 56
	v_readlane_b32 s67, v250, 57
	v_readlane_b32 s68, v250, 58
	v_readlane_b32 s69, v250, 59
	v_readlane_b32 s70, v250, 60
	v_readlane_b32 s71, v250, 61
	s_andn2_b64 vcc, exec, s[18:19]
	s_mov_b64 s[20:21], -1
	s_cbranch_vccnz .LBB0_1170
	s_andn2_b64 vcc, exec, s[12:13]
	s_cbranch_vccnz .LBB0_1169
	s_barrier
	s_branch .LBB0_1169

.LBB0_2376:
	v_readlane_b32 s0, v249, 6
	v_lshl_or_b32 v144, s50, 7, v147
	v_readlane_b32 s1, v249, 7
	v_lshl_add_u32 v153, s51, 8, v146
	v_ashrrev_i32_e32 v145, 31, v144
	v_mov_b64_e32 v[142:143], s[0:1]
	v_mad_u64_u32 v[154:155], s[20:21], v153, s39, v[142:143]
	v_lshlrev_b64 v[144:145], 1, v[144:145]
	v_lshl_add_u64 v[154:155], v[154:155], 0, v[144:145]
	v_mov_b32_e32 v192, 0xbfb8aa3b
	v_mov_b32_e32 v193, 0xbfb8aa3b
	v_mov_b32_e32 v194, 1.0
	v_mov_b32_e32 v195, 1.0
	s_mov_b64 s[22:23], 0x56000
	s_mov_b64 s[24:25], 0x1ae000
	v_pk_mul_f32 v[176:177], v[126:127], v[192:193]
	v_pk_mul_f32 v[178:179], v[128:129], v[192:193]
	v_pk_mul_f32 v[180:181], v[122:123], v[192:193]
	v_pk_mul_f32 v[182:183], v[124:125], v[192:193]
	v_exp_f32_e32 v176, v176
	v_exp_f32_e32 v177, v177
	v_exp_f32_e32 v178, v178
	v_exp_f32_e32 v179, v179
	v_exp_f32_e32 v180, v180
	v_exp_f32_e32 v181, v181
	v_exp_f32_e32 v182, v182
	v_exp_f32_e32 v183, v183
	v_pk_add_f32 v[176:177], v[176:177], v[194:195]
	v_pk_add_f32 v[178:179], v[178:179], v[194:195]
	v_pk_add_f32 v[180:181], v[180:181], v[194:195]
	v_pk_add_f32 v[182:183], v[182:183], v[194:195]
	v_rcp_f32_e32 v176, v176
	v_rcp_f32_e32 v177, v177
	v_rcp_f32_e32 v178, v178
	v_rcp_f32_e32 v179, v179
	v_rcp_f32_e32 v180, v180
	v_rcp_f32_e32 v181, v181
	v_rcp_f32_e32 v182, v182
	v_rcp_f32_e32 v183, v183
	v_lshl_add_u64 v[156:157], v[154:155], 0, s[22:23]
	v_pk_mul_f32 v[126:127], v[126:127], v[176:177]
	v_pk_mul_f32 v[128:129], v[128:129], v[178:179]
	v_pk_mul_f32 v[122:123], v[122:123], v[180:181]
	v_pk_mul_f32 v[124:125], v[124:125], v[182:183]
	v_pk_mul_f32 v[126:127], v[126:127], v[118:119]
	v_pk_mul_f32 v[128:129], v[128:129], v[120:121]
	v_pk_mul_f32 v[122:123], v[122:123], v[114:115]
	v_pk_mul_f32 v[124:125], v[124:125], v[116:117]
	v_cvt_pk_bf16_f32 v184, v126, v127
	v_cvt_pk_bf16_f32 v185, v128, v129
	v_cvt_pk_bf16_f32 v186, v122, v123
	v_cvt_pk_bf16_f32 v187, v124, v125
	global_store_dwordx4 v[154:155], v[184:187], off
	v_pk_mul_f32 v[176:177], v[110:111], v[192:193]
	v_pk_mul_f32 v[178:179], v[112:113], v[192:193]
	v_pk_mul_f32 v[180:181], v[106:107], v[192:193]
	v_pk_mul_f32 v[182:183], v[108:109], v[192:193]
	v_exp_f32_e32 v176, v176
	v_exp_f32_e32 v177, v177
	v_exp_f32_e32 v178, v178
	v_exp_f32_e32 v179, v179
	v_exp_f32_e32 v180, v180
	v_exp_f32_e32 v181, v181
	v_exp_f32_e32 v182, v182
	v_exp_f32_e32 v183, v183
	v_pk_add_f32 v[176:177], v[176:177], v[194:195]
	v_pk_add_f32 v[178:179], v[178:179], v[194:195]
	v_pk_add_f32 v[180:181], v[180:181], v[194:195]
	v_pk_add_f32 v[182:183], v[182:183], v[194:195]
	v_rcp_f32_e32 v176, v176
	v_rcp_f32_e32 v177, v177
	v_rcp_f32_e32 v178, v178
	v_rcp_f32_e32 v179, v179
	v_rcp_f32_e32 v180, v180
	v_rcp_f32_e32 v181, v181
	v_rcp_f32_e32 v182, v182
	v_rcp_f32_e32 v183, v183
	v_lshl_add_u64 v[154:155], v[156:157], 0, s[22:23]
	v_pk_mul_f32 v[110:111], v[110:111], v[176:177]
	v_pk_mul_f32 v[112:113], v[112:113], v[178:179]
	v_pk_mul_f32 v[106:107], v[106:107], v[180:181]
	v_pk_mul_f32 v[108:109], v[108:109], v[182:183]
	v_pk_mul_f32 v[110:111], v[110:111], v[102:103]
	v_pk_mul_f32 v[112:113], v[112:113], v[104:105]
	v_pk_mul_f32 v[106:107], v[106:107], v[98:99]
	v_pk_mul_f32 v[108:109], v[108:109], v[100:101]
	v_cvt_pk_bf16_f32 v188, v110, v111
	v_cvt_pk_bf16_f32 v189, v112, v113
	v_cvt_pk_bf16_f32 v190, v106, v107
	v_cvt_pk_bf16_f32 v191, v108, v109
	global_store_dwordx4 v[156:157], v[188:191], off
	v_pk_mul_f32 v[176:177], v[94:95], v[192:193]
	v_pk_mul_f32 v[178:179], v[96:97], v[192:193]
	v_pk_mul_f32 v[180:181], v[90:91], v[192:193]
	v_pk_mul_f32 v[182:183], v[92:93], v[192:193]
	v_exp_f32_e32 v176, v176
	v_exp_f32_e32 v177, v177
	v_exp_f32_e32 v178, v178
	v_exp_f32_e32 v179, v179
	v_exp_f32_e32 v180, v180
	v_exp_f32_e32 v181, v181
	v_exp_f32_e32 v182, v182
	v_exp_f32_e32 v183, v183
	v_pk_add_f32 v[176:177], v[176:177], v[194:195]
	v_pk_add_f32 v[178:179], v[178:179], v[194:195]
	v_pk_add_f32 v[180:181], v[180:181], v[194:195]
	v_pk_add_f32 v[182:183], v[182:183], v[194:195]
	v_rcp_f32_e32 v176, v176
	v_rcp_f32_e32 v177, v177
	v_rcp_f32_e32 v178, v178
	v_rcp_f32_e32 v179, v179
	v_rcp_f32_e32 v180, v180
	v_rcp_f32_e32 v181, v181
	v_rcp_f32_e32 v182, v182
	v_rcp_f32_e32 v183, v183
	v_lshl_add_u64 v[156:157], v[154:155], 0, s[22:23]
	v_pk_mul_f32 v[94:95], v[94:95], v[176:177]
	v_pk_mul_f32 v[96:97], v[96:97], v[178:179]
	v_pk_mul_f32 v[90:91], v[90:91], v[180:181]
	v_pk_mul_f32 v[92:93], v[92:93], v[182:183]
	v_pk_mul_f32 v[94:95], v[94:95], v[86:87]
	v_pk_mul_f32 v[96:97], v[96:97], v[88:89]
	v_pk_mul_f32 v[90:91], v[90:91], v[82:83]
	v_pk_mul_f32 v[92:93], v[92:93], v[84:85]
	v_cvt_pk_bf16_f32 v184, v94, v95
	v_cvt_pk_bf16_f32 v185, v96, v97
	v_cvt_pk_bf16_f32 v186, v90, v91
	v_cvt_pk_bf16_f32 v187, v92, v93
	global_store_dwordx4 v[154:155], v[184:187], off
	v_pk_mul_f32 v[176:177], v[78:79], v[192:193]
	v_pk_mul_f32 v[178:179], v[80:81], v[192:193]
	v_pk_mul_f32 v[180:181], v[74:75], v[192:193]
	v_pk_mul_f32 v[182:183], v[76:77], v[192:193]
	v_exp_f32_e32 v176, v176
	v_exp_f32_e32 v177, v177
	v_exp_f32_e32 v178, v178
	v_exp_f32_e32 v179, v179
	v_exp_f32_e32 v180, v180
	v_exp_f32_e32 v181, v181
	v_exp_f32_e32 v182, v182
	v_exp_f32_e32 v183, v183
	v_pk_add_f32 v[176:177], v[176:177], v[194:195]
	v_pk_add_f32 v[178:179], v[178:179], v[194:195]
	v_pk_add_f32 v[180:181], v[180:181], v[194:195]
	v_pk_add_f32 v[182:183], v[182:183], v[194:195]
	v_rcp_f32_e32 v176, v176
	v_rcp_f32_e32 v177, v177
	v_rcp_f32_e32 v178, v178
	v_rcp_f32_e32 v179, v179
	v_rcp_f32_e32 v180, v180
	v_rcp_f32_e32 v181, v181
	v_rcp_f32_e32 v182, v182
	v_rcp_f32_e32 v183, v183
	v_lshl_add_u64 v[154:155], v[156:157], 0, s[24:25]
	v_pk_mul_f32 v[78:79], v[78:79], v[176:177]
	v_pk_mul_f32 v[80:81], v[80:81], v[178:179]
	v_pk_mul_f32 v[74:75], v[74:75], v[180:181]
	v_pk_mul_f32 v[76:77], v[76:77], v[182:183]
	v_pk_mul_f32 v[78:79], v[78:79], v[70:71]
	v_pk_mul_f32 v[80:81], v[80:81], v[72:73]
	v_pk_mul_f32 v[74:75], v[74:75], v[66:67]
	v_pk_mul_f32 v[76:77], v[76:77], v[68:69]
	v_cvt_pk_bf16_f32 v188, v78, v79
	v_cvt_pk_bf16_f32 v189, v80, v81
	v_cvt_pk_bf16_f32 v190, v74, v75
	v_cvt_pk_bf16_f32 v191, v76, v77
	global_store_dwordx4 v[156:157], v[188:191], off
	v_pk_mul_f32 v[176:177], v[62:63], v[192:193]
	v_pk_mul_f32 v[178:179], v[64:65], v[192:193]
	v_pk_mul_f32 v[180:181], v[58:59], v[192:193]
	v_pk_mul_f32 v[182:183], v[60:61], v[192:193]
	v_exp_f32_e32 v176, v176
	v_exp_f32_e32 v177, v177
	v_exp_f32_e32 v178, v178
	v_exp_f32_e32 v179, v179
	v_exp_f32_e32 v180, v180
	v_exp_f32_e32 v181, v181
	v_exp_f32_e32 v182, v182
	v_exp_f32_e32 v183, v183
	v_pk_add_f32 v[176:177], v[176:177], v[194:195]
	v_pk_add_f32 v[178:179], v[178:179], v[194:195]
	v_pk_add_f32 v[180:181], v[180:181], v[194:195]
	v_pk_add_f32 v[182:183], v[182:183], v[194:195]
	v_rcp_f32_e32 v176, v176
	v_rcp_f32_e32 v177, v177
	v_rcp_f32_e32 v178, v178
	v_rcp_f32_e32 v179, v179
	v_rcp_f32_e32 v180, v180
	v_rcp_f32_e32 v181, v181
	v_rcp_f32_e32 v182, v182
	v_rcp_f32_e32 v183, v183
	v_lshl_add_u64 v[156:157], v[154:155], 0, s[22:23]
	v_pk_mul_f32 v[62:63], v[62:63], v[176:177]
	v_pk_mul_f32 v[64:65], v[64:65], v[178:179]
	v_pk_mul_f32 v[58:59], v[58:59], v[180:181]
	v_pk_mul_f32 v[60:61], v[60:61], v[182:183]
	v_pk_mul_f32 v[62:63], v[62:63], v[54:55]
	v_pk_mul_f32 v[64:65], v[64:65], v[56:57]
	v_pk_mul_f32 v[58:59], v[58:59], v[50:51]
	v_pk_mul_f32 v[60:61], v[60:61], v[52:53]
	v_cvt_pk_bf16_f32 v184, v62, v63
	v_cvt_pk_bf16_f32 v185, v64, v65
	v_cvt_pk_bf16_f32 v186, v58, v59
	v_cvt_pk_bf16_f32 v187, v60, v61
	global_store_dwordx4 v[154:155], v[184:187], off
	v_pk_mul_f32 v[176:177], v[46:47], v[192:193]
	v_pk_mul_f32 v[178:179], v[48:49], v[192:193]
	v_pk_mul_f32 v[180:181], v[42:43], v[192:193]
	v_pk_mul_f32 v[182:183], v[44:45], v[192:193]
	v_exp_f32_e32 v176, v176
	v_exp_f32_e32 v177, v177
	v_exp_f32_e32 v178, v178
	v_exp_f32_e32 v179, v179
	v_exp_f32_e32 v180, v180
	v_exp_f32_e32 v181, v181
	v_exp_f32_e32 v182, v182
	v_exp_f32_e32 v183, v183
	v_pk_add_f32 v[176:177], v[176:177], v[194:195]
	v_pk_add_f32 v[178:179], v[178:179], v[194:195]
	v_pk_add_f32 v[180:181], v[180:181], v[194:195]
	v_pk_add_f32 v[182:183], v[182:183], v[194:195]
	v_rcp_f32_e32 v176, v176
	v_rcp_f32_e32 v177, v177
	v_rcp_f32_e32 v178, v178
	v_rcp_f32_e32 v179, v179
	v_rcp_f32_e32 v180, v180
	v_rcp_f32_e32 v181, v181
	v_rcp_f32_e32 v182, v182
	v_rcp_f32_e32 v183, v183
	v_lshl_add_u64 v[154:155], v[156:157], 0, s[22:23]
	v_pk_mul_f32 v[46:47], v[46:47], v[176:177]
	v_pk_mul_f32 v[48:49], v[48:49], v[178:179]
	v_pk_mul_f32 v[42:43], v[42:43], v[180:181]
	v_pk_mul_f32 v[44:45], v[44:45], v[182:183]
	v_pk_mul_f32 v[46:47], v[46:47], v[38:39]
	v_pk_mul_f32 v[48:49], v[48:49], v[40:41]
	v_pk_mul_f32 v[42:43], v[42:43], v[34:35]
	v_pk_mul_f32 v[44:45], v[44:45], v[36:37]
	v_cvt_pk_bf16_f32 v188, v46, v47
	v_cvt_pk_bf16_f32 v189, v48, v49
	v_cvt_pk_bf16_f32 v190, v42, v43
	v_cvt_pk_bf16_f32 v191, v44, v45
	global_store_dwordx4 v[156:157], v[188:191], off
	v_pk_mul_f32 v[176:177], v[30:31], v[192:193]
	v_pk_mul_f32 v[178:179], v[32:33], v[192:193]
	v_pk_mul_f32 v[180:181], v[26:27], v[192:193]
	v_pk_mul_f32 v[182:183], v[28:29], v[192:193]
	v_exp_f32_e32 v176, v176
	v_exp_f32_e32 v177, v177
	v_exp_f32_e32 v178, v178
	v_exp_f32_e32 v179, v179
	v_exp_f32_e32 v180, v180
	v_exp_f32_e32 v181, v181
	v_exp_f32_e32 v182, v182
	v_exp_f32_e32 v183, v183
	v_pk_add_f32 v[176:177], v[176:177], v[194:195]
	v_pk_add_f32 v[178:179], v[178:179], v[194:195]
	v_pk_add_f32 v[180:181], v[180:181], v[194:195]
	v_pk_add_f32 v[182:183], v[182:183], v[194:195]
	v_rcp_f32_e32 v176, v176
	v_rcp_f32_e32 v177, v177
	v_rcp_f32_e32 v178, v178
	v_rcp_f32_e32 v179, v179
	v_rcp_f32_e32 v180, v180
	v_rcp_f32_e32 v181, v181
	v_rcp_f32_e32 v182, v182
	v_rcp_f32_e32 v183, v183
	v_lshl_add_u64 v[156:157], v[154:155], 0, s[22:23]
	v_pk_mul_f32 v[30:31], v[30:31], v[176:177]
	v_pk_mul_f32 v[32:33], v[32:33], v[178:179]
	v_pk_mul_f32 v[26:27], v[26:27], v[180:181]
	v_pk_mul_f32 v[28:29], v[28:29], v[182:183]
	v_pk_mul_f32 v[30:31], v[30:31], v[22:23]
	v_pk_mul_f32 v[32:33], v[32:33], v[24:25]
	v_pk_mul_f32 v[26:27], v[26:27], v[18:19]
	v_pk_mul_f32 v[28:29], v[28:29], v[20:21]
	v_cvt_pk_bf16_f32 v184, v30, v31
	v_cvt_pk_bf16_f32 v185, v32, v33
	v_cvt_pk_bf16_f32 v186, v26, v27
	v_cvt_pk_bf16_f32 v187, v28, v29
	global_store_dwordx4 v[154:155], v[184:187], off
	v_pk_mul_f32 v[176:177], v[14:15], v[192:193]
	v_pk_mul_f32 v[178:179], v[16:17], v[192:193]
	v_pk_mul_f32 v[180:181], v[10:11], v[192:193]
	v_pk_mul_f32 v[182:183], v[12:13], v[192:193]
	v_exp_f32_e32 v176, v176
	v_exp_f32_e32 v177, v177
	v_exp_f32_e32 v178, v178
	v_exp_f32_e32 v179, v179
	v_exp_f32_e32 v180, v180
	v_exp_f32_e32 v181, v181
	v_exp_f32_e32 v182, v182
	v_exp_f32_e32 v183, v183
	v_pk_add_f32 v[176:177], v[176:177], v[194:195]
	v_pk_add_f32 v[178:179], v[178:179], v[194:195]
	v_pk_add_f32 v[180:181], v[180:181], v[194:195]
	v_pk_add_f32 v[182:183], v[182:183], v[194:195]
	v_rcp_f32_e32 v176, v176
	v_rcp_f32_e32 v177, v177
	v_rcp_f32_e32 v178, v178
	v_rcp_f32_e32 v179, v179
	v_rcp_f32_e32 v180, v180
	v_rcp_f32_e32 v181, v181
	v_rcp_f32_e32 v182, v182
	v_rcp_f32_e32 v183, v183
	s_nop 0
	v_pk_mul_f32 v[14:15], v[14:15], v[176:177]
	v_pk_mul_f32 v[16:17], v[16:17], v[178:179]
	v_pk_mul_f32 v[10:11], v[10:11], v[180:181]
	v_pk_mul_f32 v[12:13], v[12:13], v[182:183]
	v_pk_mul_f32 v[14:15], v[14:15], v[6:7]
	v_pk_mul_f32 v[16:17], v[16:17], v[8:9]
	v_pk_mul_f32 v[10:11], v[10:11], v[2:3]
	v_pk_mul_f32 v[12:13], v[12:13], v[4:5]
	v_cvt_pk_bf16_f32 v188, v14, v15
	v_cvt_pk_bf16_f32 v189, v16, v17
	v_cvt_pk_bf16_f32 v190, v10, v11
	v_cvt_pk_bf16_f32 v191, v12, v13
	global_store_dwordx4 v[156:157], v[188:191], off
	v_readlane_b32 s60, v250, 50
	v_readlane_b32 s72, v250, 62
	v_readlane_b32 s73, v250, 63
	v_readlane_b32 s61, v250, 51
	v_readlane_b32 s62, v250, 52
	v_readlane_b32 s63, v250, 53
	v_readlane_b32 s64, v250, 54
	v_readlane_b32 s65, v250, 55
	v_readlane_b32 s66, v250, 56
	v_readlane_b32 s67, v250, 57
	v_readlane_b32 s68, v250, 58
	v_readlane_b32 s69, v250, 59
	v_readlane_b32 s70, v250, 60
	v_readlane_b32 s71, v250, 61
	v_readlane_b32 s74, v249, 0
	v_readlane_b32 s75, v249, 1
	s_andn2_b64 vcc, exec, s[18:19]
	s_mov_b64 s[18:19], -1
	s_cbranch_vccnz .LBB0_2371
	s_andn2_b64 vcc, exec, s[12:13]
	s_cbranch_vccnz .LBB0_2370
	s_barrier
	s_branch .LBB0_2370
